# snake MFMA order plus straight-line silu table (20 loads in flight) and modreduce with all 32 partial loads issued up front
# baseline (speedup 1.0000x reference)
.LBB0_15:
	s_lshr_b32 s58, s8, 6
	s_cmp_lt_i32 s70, 1
	s_cselect_b64 s[2:3], -1, 0
	s_cmp_gt_i32 s71, 0
	s_cselect_b64 s[4:5], -1, 0
	s_and_b64 s[4:5], s[2:3], s[4:5]
	s_andn2_b64 vcc, exec, s[4:5]
	v_writelane_b32 v253, s58, 5
	s_cbranch_vccnz .LBB0_780
	s_mov_b32 s16, 0
	s_mov_b32 s20, s58
	s_mov_b64 s[6:7], s[68:69]
	s_mov_b32 s17, s89
	s_mov_b32 s33, s88
	v_mov_b32_e32 v1, v0
	s_movk_i32 s2, 0x2800
	s_nop 0
	v_cmp_gt_i32_e32 vcc, s2, v1
	s_and_saveexec_b64 s[2:3], vcc
	s_cbranch_execz .LBB0_23
	v_lshl_add_u32 v6, v1, 2, s16
	v_lshlrev_b32_e32 v7, 2, v1
	s_load_dwordx2 s[10:11], s[0:1], 48
	s_load_dwordx2 s[12:13], s[0:1], 56
	s_waitcnt lgkmcnt(0)
	global_load_dword v8, v7, s[12:13]
	global_load_dword v9, v7, s[12:13] offset:2048
	s_add_u32 s12, s12, 0x1000
	s_addc_u32 s13, s13, 0
	global_load_dword v10, v7, s[12:13]
	global_load_dword v11, v7, s[12:13] offset:2048
	global_load_dword v12, v7, s[10:11]
	global_load_dword v13, v7, s[10:11] offset:2048
	s_add_u32 s10, s10, 0x1000
	s_addc_u32 s11, s11, 0
	global_load_dword v14, v7, s[10:11]
	global_load_dword v15, v7, s[10:11] offset:2048
	s_add_u32 s10, s10, 0x1000
	s_addc_u32 s11, s11, 0
	global_load_dword v16, v7, s[10:11]
	global_load_dword v17, v7, s[10:11] offset:2048
	s_add_u32 s10, s10, 0x1000
	s_addc_u32 s11, s11, 0
	global_load_dword v18, v7, s[10:11]
	global_load_dword v19, v7, s[10:11] offset:2048
	s_add_u32 s10, s10, 0x1000
	s_addc_u32 s11, s11, 0
	global_load_dword v20, v7, s[10:11]
	global_load_dword v21, v7, s[10:11] offset:2048
	s_add_u32 s10, s10, 0x1000
	s_addc_u32 s11, s11, 0
	global_load_dword v22, v7, s[10:11]
	global_load_dword v23, v7, s[10:11] offset:2048
	s_add_u32 s10, s10, 0x1000
	s_addc_u32 s11, s11, 0
	global_load_dword v24, v7, s[10:11]
	global_load_dword v25, v7, s[10:11] offset:2048
	s_add_u32 s10, s10, 0x1000
	s_addc_u32 s11, s11, 0
	global_load_dword v26, v7, s[10:11]
	global_load_dword v27, v7, s[10:11] offset:2048
	s_waitcnt vmcnt(19)
	v_mul_f32_e32 v3, 0xbfb8aa3b, v8
	v_exp_f32_e32 v3, v3
	s_nop 0
	v_add_f32_e32 v3, 1.0, v3
	v_div_scale_f32 v4, s[14:15], v3, v3, v8
	v_rcp_f32_e32 v5, v4
	v_div_scale_f32 v28, vcc, v8, v3, v8
	v_fma_f32 v29, -v4, v5, 1.0
	v_fmac_f32_e32 v5, v29, v5
	v_mul_f32_e32 v29, v28, v5
	v_fma_f32 v30, -v4, v29, v28
	v_fmac_f32_e32 v29, v30, v5
	v_fma_f32 v4, -v4, v29, v28
	v_div_fmas_f32 v4, v4, v5, v29
	v_div_fixup_f32 v2, v4, v3, v8
	ds_write_b32 v6, v2
	s_waitcnt vmcnt(18)
	v_mul_f32_e32 v3, 0xbfb8aa3b, v9
	v_exp_f32_e32 v3, v3
	s_nop 0
	v_add_f32_e32 v3, 1.0, v3
	v_div_scale_f32 v4, s[14:15], v3, v3, v9
	v_rcp_f32_e32 v5, v4
	v_div_scale_f32 v28, vcc, v9, v3, v9
	v_fma_f32 v29, -v4, v5, 1.0
	v_fmac_f32_e32 v5, v29, v5
	v_mul_f32_e32 v29, v28, v5
	v_fma_f32 v30, -v4, v29, v28
	v_fmac_f32_e32 v29, v30, v5
	v_fma_f32 v4, -v4, v29, v28
	v_div_fmas_f32 v4, v4, v5, v29
	v_div_fixup_f32 v2, v4, v3, v9
	ds_write_b32 v6, v2 offset:2048
	s_waitcnt vmcnt(17)
	v_mul_f32_e32 v3, 0xbfb8aa3b, v10
	v_exp_f32_e32 v3, v3
	s_nop 0
	v_add_f32_e32 v3, 1.0, v3
	v_div_scale_f32 v4, s[14:15], v3, v3, v10
	v_rcp_f32_e32 v5, v4
	v_div_scale_f32 v28, vcc, v10, v3, v10
	v_fma_f32 v29, -v4, v5, 1.0
	v_fmac_f32_e32 v5, v29, v5
	v_mul_f32_e32 v29, v28, v5
	v_fma_f32 v30, -v4, v29, v28
	v_fmac_f32_e32 v29, v30, v5
	v_fma_f32 v4, -v4, v29, v28
	v_div_fmas_f32 v4, v4, v5, v29
	v_div_fixup_f32 v2, v4, v3, v10
	ds_write_b32 v6, v2 offset:4096
	s_waitcnt vmcnt(16)
	v_mul_f32_e32 v3, 0xbfb8aa3b, v11
	v_exp_f32_e32 v3, v3
	s_nop 0
	v_add_f32_e32 v3, 1.0, v3
	v_div_scale_f32 v4, s[14:15], v3, v3, v11
	v_rcp_f32_e32 v5, v4
	v_div_scale_f32 v28, vcc, v11, v3, v11
	v_fma_f32 v29, -v4, v5, 1.0
	v_fmac_f32_e32 v5, v29, v5
	v_mul_f32_e32 v29, v28, v5
	v_fma_f32 v30, -v4, v29, v28
	v_fmac_f32_e32 v29, v30, v5
	v_fma_f32 v4, -v4, v29, v28
	v_div_fmas_f32 v4, v4, v5, v29
	v_div_fixup_f32 v2, v4, v3, v11
	ds_write_b32 v6, v2 offset:6144
	s_waitcnt vmcnt(15)
	v_mul_f32_e32 v3, 0xbfb8aa3b, v12
	v_exp_f32_e32 v3, v3
	s_nop 0
	v_add_f32_e32 v3, 1.0, v3
	v_div_scale_f32 v4, s[14:15], v3, v3, v12
	v_rcp_f32_e32 v5, v4
	v_div_scale_f32 v28, vcc, v12, v3, v12
	v_fma_f32 v29, -v4, v5, 1.0
	v_fmac_f32_e32 v5, v29, v5
	v_mul_f32_e32 v29, v28, v5
	v_fma_f32 v30, -v4, v29, v28
	v_fmac_f32_e32 v29, v30, v5
	v_fma_f32 v4, -v4, v29, v28
	v_div_fmas_f32 v4, v4, v5, v29
	v_div_fixup_f32 v2, v4, v3, v12
	ds_write_b32 v6, v2 offset:8192
	s_waitcnt vmcnt(14)
	v_mul_f32_e32 v3, 0xbfb8aa3b, v13
	v_exp_f32_e32 v3, v3
	s_nop 0
	v_add_f32_e32 v3, 1.0, v3
	v_div_scale_f32 v4, s[14:15], v3, v3, v13
	v_rcp_f32_e32 v5, v4
	v_div_scale_f32 v28, vcc, v13, v3, v13
	v_fma_f32 v29, -v4, v5, 1.0
	v_fmac_f32_e32 v5, v29, v5
	v_mul_f32_e32 v29, v28, v5
	v_fma_f32 v30, -v4, v29, v28
	v_fmac_f32_e32 v29, v30, v5
	v_fma_f32 v4, -v4, v29, v28
	v_div_fmas_f32 v4, v4, v5, v29
	v_div_fixup_f32 v2, v4, v3, v13
	ds_write_b32 v6, v2 offset:10240
	s_waitcnt vmcnt(13)
	v_mul_f32_e32 v3, 0xbfb8aa3b, v14
	v_exp_f32_e32 v3, v3
	s_nop 0
	v_add_f32_e32 v3, 1.0, v3
	v_div_scale_f32 v4, s[14:15], v3, v3, v14
	v_rcp_f32_e32 v5, v4
	v_div_scale_f32 v28, vcc, v14, v3, v14
	v_fma_f32 v29, -v4, v5, 1.0
	v_fmac_f32_e32 v5, v29, v5
	v_mul_f32_e32 v29, v28, v5
	v_fma_f32 v30, -v4, v29, v28
	v_fmac_f32_e32 v29, v30, v5
	v_fma_f32 v4, -v4, v29, v28
	v_div_fmas_f32 v4, v4, v5, v29
	v_div_fixup_f32 v2, v4, v3, v14
	ds_write_b32 v6, v2 offset:12288
	s_waitcnt vmcnt(12)
	v_mul_f32_e32 v3, 0xbfb8aa3b, v15
	v_exp_f32_e32 v3, v3
	s_nop 0
	v_add_f32_e32 v3, 1.0, v3
	v_div_scale_f32 v4, s[14:15], v3, v3, v15
	v_rcp_f32_e32 v5, v4
	v_div_scale_f32 v28, vcc, v15, v3, v15
	v_fma_f32 v29, -v4, v5, 1.0
	v_fmac_f32_e32 v5, v29, v5
	v_mul_f32_e32 v29, v28, v5
	v_fma_f32 v30, -v4, v29, v28
	v_fmac_f32_e32 v29, v30, v5
	v_fma_f32 v4, -v4, v29, v28
	v_div_fmas_f32 v4, v4, v5, v29
	v_div_fixup_f32 v2, v4, v3, v15
	ds_write_b32 v6, v2 offset:14336
	s_waitcnt vmcnt(11)
	v_mul_f32_e32 v3, 0xbfb8aa3b, v16
	v_exp_f32_e32 v3, v3
	s_nop 0
	v_add_f32_e32 v3, 1.0, v3
	v_div_scale_f32 v4, s[14:15], v3, v3, v16
	v_rcp_f32_e32 v5, v4
	v_div_scale_f32 v28, vcc, v16, v3, v16
	v_fma_f32 v29, -v4, v5, 1.0
	v_fmac_f32_e32 v5, v29, v5
	v_mul_f32_e32 v29, v28, v5
	v_fma_f32 v30, -v4, v29, v28
	v_fmac_f32_e32 v29, v30, v5
	v_fma_f32 v4, -v4, v29, v28
	v_div_fmas_f32 v4, v4, v5, v29
	v_div_fixup_f32 v2, v4, v3, v16
	ds_write_b32 v6, v2 offset:16384
	s_waitcnt vmcnt(10)
	v_mul_f32_e32 v3, 0xbfb8aa3b, v17
	v_exp_f32_e32 v3, v3
	s_nop 0
	v_add_f32_e32 v3, 1.0, v3
	v_div_scale_f32 v4, s[14:15], v3, v3, v17
	v_rcp_f32_e32 v5, v4
	v_div_scale_f32 v28, vcc, v17, v3, v17
	v_fma_f32 v29, -v4, v5, 1.0
	v_fmac_f32_e32 v5, v29, v5
	v_mul_f32_e32 v29, v28, v5
	v_fma_f32 v30, -v4, v29, v28
	v_fmac_f32_e32 v29, v30, v5
	v_fma_f32 v4, -v4, v29, v28
	v_div_fmas_f32 v4, v4, v5, v29
	v_div_fixup_f32 v2, v4, v3, v17
	ds_write_b32 v6, v2 offset:18432
	s_waitcnt vmcnt(9)
	v_mul_f32_e32 v3, 0xbfb8aa3b, v18
	v_exp_f32_e32 v3, v3
	s_nop 0
	v_add_f32_e32 v3, 1.0, v3
	v_div_scale_f32 v4, s[14:15], v3, v3, v18
	v_rcp_f32_e32 v5, v4
	v_div_scale_f32 v28, vcc, v18, v3, v18
	v_fma_f32 v29, -v4, v5, 1.0
	v_fmac_f32_e32 v5, v29, v5
	v_mul_f32_e32 v29, v28, v5
	v_fma_f32 v30, -v4, v29, v28
	v_fmac_f32_e32 v29, v30, v5
	v_fma_f32 v4, -v4, v29, v28
	v_div_fmas_f32 v4, v4, v5, v29
	v_div_fixup_f32 v2, v4, v3, v18
	ds_write_b32 v6, v2 offset:20480
	s_waitcnt vmcnt(8)
	v_mul_f32_e32 v3, 0xbfb8aa3b, v19
	v_exp_f32_e32 v3, v3
	s_nop 0
	v_add_f32_e32 v3, 1.0, v3
	v_div_scale_f32 v4, s[14:15], v3, v3, v19
	v_rcp_f32_e32 v5, v4
	v_div_scale_f32 v28, vcc, v19, v3, v19
	v_fma_f32 v29, -v4, v5, 1.0
	v_fmac_f32_e32 v5, v29, v5
	v_mul_f32_e32 v29, v28, v5
	v_fma_f32 v30, -v4, v29, v28
	v_fmac_f32_e32 v29, v30, v5
	v_fma_f32 v4, -v4, v29, v28
	v_div_fmas_f32 v4, v4, v5, v29
	v_div_fixup_f32 v2, v4, v3, v19
	ds_write_b32 v6, v2 offset:22528
	s_waitcnt vmcnt(7)
	v_mul_f32_e32 v3, 0xbfb8aa3b, v20
	v_exp_f32_e32 v3, v3
	s_nop 0
	v_add_f32_e32 v3, 1.0, v3
	v_div_scale_f32 v4, s[14:15], v3, v3, v20
	v_rcp_f32_e32 v5, v4
	v_div_scale_f32 v28, vcc, v20, v3, v20
	v_fma_f32 v29, -v4, v5, 1.0
	v_fmac_f32_e32 v5, v29, v5
	v_mul_f32_e32 v29, v28, v5
	v_fma_f32 v30, -v4, v29, v28
	v_fmac_f32_e32 v29, v30, v5
	v_fma_f32 v4, -v4, v29, v28
	v_div_fmas_f32 v4, v4, v5, v29
	v_div_fixup_f32 v2, v4, v3, v20
	ds_write_b32 v6, v2 offset:24576
	s_waitcnt vmcnt(6)
	v_mul_f32_e32 v3, 0xbfb8aa3b, v21
	v_exp_f32_e32 v3, v3
	s_nop 0
	v_add_f32_e32 v3, 1.0, v3
	v_div_scale_f32 v4, s[14:15], v3, v3, v21
	v_rcp_f32_e32 v5, v4
	v_div_scale_f32 v28, vcc, v21, v3, v21
	v_fma_f32 v29, -v4, v5, 1.0
	v_fmac_f32_e32 v5, v29, v5
	v_mul_f32_e32 v29, v28, v5
	v_fma_f32 v30, -v4, v29, v28
	v_fmac_f32_e32 v29, v30, v5
	v_fma_f32 v4, -v4, v29, v28
	v_div_fmas_f32 v4, v4, v5, v29
	v_div_fixup_f32 v2, v4, v3, v21
	ds_write_b32 v6, v2 offset:26624
	s_waitcnt vmcnt(5)
	v_mul_f32_e32 v3, 0xbfb8aa3b, v22
	v_exp_f32_e32 v3, v3
	s_nop 0
	v_add_f32_e32 v3, 1.0, v3
	v_div_scale_f32 v4, s[14:15], v3, v3, v22
	v_rcp_f32_e32 v5, v4
	v_div_scale_f32 v28, vcc, v22, v3, v22
	v_fma_f32 v29, -v4, v5, 1.0
	v_fmac_f32_e32 v5, v29, v5
	v_mul_f32_e32 v29, v28, v5
	v_fma_f32 v30, -v4, v29, v28
	v_fmac_f32_e32 v29, v30, v5
	v_fma_f32 v4, -v4, v29, v28
	v_div_fmas_f32 v4, v4, v5, v29
	v_div_fixup_f32 v2, v4, v3, v22
	ds_write_b32 v6, v2 offset:28672
	s_waitcnt vmcnt(4)
	v_mul_f32_e32 v3, 0xbfb8aa3b, v23
	v_exp_f32_e32 v3, v3
	s_nop 0
	v_add_f32_e32 v3, 1.0, v3
	v_div_scale_f32 v4, s[14:15], v3, v3, v23
	v_rcp_f32_e32 v5, v4
	v_div_scale_f32 v28, vcc, v23, v3, v23
	v_fma_f32 v29, -v4, v5, 1.0
	v_fmac_f32_e32 v5, v29, v5
	v_mul_f32_e32 v29, v28, v5
	v_fma_f32 v30, -v4, v29, v28
	v_fmac_f32_e32 v29, v30, v5
	v_fma_f32 v4, -v4, v29, v28
	v_div_fmas_f32 v4, v4, v5, v29
	v_div_fixup_f32 v2, v4, v3, v23
	ds_write_b32 v6, v2 offset:30720
	s_waitcnt vmcnt(3)
	v_mul_f32_e32 v3, 0xbfb8aa3b, v24
	v_exp_f32_e32 v3, v3
	s_nop 0
	v_add_f32_e32 v3, 1.0, v3
	v_div_scale_f32 v4, s[14:15], v3, v3, v24
	v_rcp_f32_e32 v5, v4
	v_div_scale_f32 v28, vcc, v24, v3, v24
	v_fma_f32 v29, -v4, v5, 1.0
	v_fmac_f32_e32 v5, v29, v5
	v_mul_f32_e32 v29, v28, v5
	v_fma_f32 v30, -v4, v29, v28
	v_fmac_f32_e32 v29, v30, v5
	v_fma_f32 v4, -v4, v29, v28
	v_div_fmas_f32 v4, v4, v5, v29
	v_div_fixup_f32 v2, v4, v3, v24
	ds_write_b32 v6, v2 offset:32768
	s_waitcnt vmcnt(2)
	v_mul_f32_e32 v3, 0xbfb8aa3b, v25
	v_exp_f32_e32 v3, v3
	s_nop 0
	v_add_f32_e32 v3, 1.0, v3
	v_div_scale_f32 v4, s[14:15], v3, v3, v25
	v_rcp_f32_e32 v5, v4
	v_div_scale_f32 v28, vcc, v25, v3, v25
	v_fma_f32 v29, -v4, v5, 1.0
	v_fmac_f32_e32 v5, v29, v5
	v_mul_f32_e32 v29, v28, v5
	v_fma_f32 v30, -v4, v29, v28
	v_fmac_f32_e32 v29, v30, v5
	v_fma_f32 v4, -v4, v29, v28
	v_div_fmas_f32 v4, v4, v5, v29
	v_div_fixup_f32 v2, v4, v3, v25
	ds_write_b32 v6, v2 offset:34816
	s_waitcnt vmcnt(1)
	v_mul_f32_e32 v3, 0xbfb8aa3b, v26
	v_exp_f32_e32 v3, v3
	s_nop 0
	v_add_f32_e32 v3, 1.0, v3
	v_div_scale_f32 v4, s[14:15], v3, v3, v26
	v_rcp_f32_e32 v5, v4
	v_div_scale_f32 v28, vcc, v26, v3, v26
	v_fma_f32 v29, -v4, v5, 1.0
	v_fmac_f32_e32 v5, v29, v5
	v_mul_f32_e32 v29, v28, v5
	v_fma_f32 v30, -v4, v29, v28
	v_fmac_f32_e32 v29, v30, v5
	v_fma_f32 v4, -v4, v29, v28
	v_div_fmas_f32 v4, v4, v5, v29
	v_div_fixup_f32 v2, v4, v3, v26
	ds_write_b32 v6, v2 offset:36864
	s_waitcnt vmcnt(0)
	v_mul_f32_e32 v3, 0xbfb8aa3b, v27
	v_exp_f32_e32 v3, v3
	s_nop 0
	v_add_f32_e32 v3, 1.0, v3
	v_div_scale_f32 v4, s[14:15], v3, v3, v27
	v_rcp_f32_e32 v5, v4
	v_div_scale_f32 v28, vcc, v27, v3, v27
	v_fma_f32 v29, -v4, v5, 1.0
	v_fmac_f32_e32 v5, v29, v5
	v_mul_f32_e32 v29, v28, v5
	v_fma_f32 v30, -v4, v29, v28
	v_fmac_f32_e32 v29, v30, v5
	v_fma_f32 v4, -v4, v29, v28
	v_div_fmas_f32 v4, v4, v5, v29
	v_div_fixup_f32 v2, v4, v3, v27
	ds_write_b32 v6, v2 offset:38912

.LBB0_837:
	s_waitcnt vmcnt(1)
	v_mul_hi_i32 v2, v1, s15
	v_lshrrev_b32_e32 v3, 31, v2
	v_ashrrev_i32_e32 v2, 9, v2
	v_add_u32_e32 v10, v2, v3
	v_mul_i32_i24_e32 v2, 0xc00, v10
	v_sub_u32_e32 v4, v1, v2
	v_mul_hi_i32 v2, v1, s16
	v_add_u32_e32 v2, v2, v1
	v_lshrrev_b32_e32 v3, 31, v2
	v_ashrrev_i32_e32 v2, 13, v2
	v_add_u32_e32 v2, v2, v3
	s_waitcnt vmcnt(0)
	v_lshlrev_b32_e32 v6, 2, v4
	v_mul_hi_i32_i24_e32 v3, 0xc000, v2
	v_mul_i32_i24_e32 v2, 0xc000, v2
	v_ashrrev_i32_e32 v7, 31, v6
	s_load_dwordx2 s[12:13], s[0:1], 0x48
	s_waitcnt lgkmcnt(0)
	v_lshlrev_b64 v[8:9], 2, v[6:7]
	v_lshl_add_u64 v[2:3], s[12:13], 0, v[2:3]
	v_lshl_add_u64 v[2:3], v[2:3], 0, v[8:9]
	global_load_dwordx4 v[2:5], v[2:3], off
	v_mad_i64_i32 v[8:9], s[12:13], v10, s17, v[8:9]
	v_lshl_add_u64 v[8:9], s[4:5], 0, v[8:9]
	s_mov_b64 s[12:13], 0
	s_mov_b32 s12, 0x200000
	s_mov_b32 s13, 0
	v_lshl_add_u64 v[20:21], v[8:9], 0, s[12:13]
	s_add_u32 s12, s12, 0xf0000
	s_addc_u32 s13, s13, 0
	global_load_dwordx4 v[32:35], v[20:21], off
	v_lshl_add_u64 v[22:23], v[8:9], 0, s[12:13]
	s_add_u32 s12, s12, 0xf0000
	s_addc_u32 s13, s13, 0
	global_load_dwordx4 v[36:39], v[22:23], off
	v_lshl_add_u64 v[20:21], v[8:9], 0, s[12:13]
	s_add_u32 s12, s12, 0xf0000
	s_addc_u32 s13, s13, 0
	global_load_dwordx4 v[40:43], v[20:21], off
	v_lshl_add_u64 v[22:23], v[8:9], 0, s[12:13]
	s_add_u32 s12, s12, 0xf0000
	s_addc_u32 s13, s13, 0
	global_load_dwordx4 v[44:47], v[22:23], off
	v_lshl_add_u64 v[20:21], v[8:9], 0, s[12:13]
	s_add_u32 s12, s12, 0xf0000
	s_addc_u32 s13, s13, 0
	global_load_dwordx4 v[48:51], v[20:21], off
	v_lshl_add_u64 v[22:23], v[8:9], 0, s[12:13]
	s_add_u32 s12, s12, 0xf0000
	s_addc_u32 s13, s13, 0
	global_load_dwordx4 v[52:55], v[22:23], off
	v_lshl_add_u64 v[20:21], v[8:9], 0, s[12:13]
	s_add_u32 s12, s12, 0xf0000
	s_addc_u32 s13, s13, 0
	global_load_dwordx4 v[56:59], v[20:21], off
	v_lshl_add_u64 v[22:23], v[8:9], 0, s[12:13]
	s_add_u32 s12, s12, 0xf0000
	s_addc_u32 s13, s13, 0
	global_load_dwordx4 v[60:63], v[22:23], off
	v_lshl_add_u64 v[20:21], v[8:9], 0, s[12:13]
	s_add_u32 s12, s12, 0xf0000
	s_addc_u32 s13, s13, 0
	global_load_dwordx4 v[64:67], v[20:21], off
	v_lshl_add_u64 v[22:23], v[8:9], 0, s[12:13]
	s_add_u32 s12, s12, 0xf0000
	s_addc_u32 s13, s13, 0
	global_load_dwordx4 v[68:71], v[22:23], off
	v_lshl_add_u64 v[20:21], v[8:9], 0, s[12:13]
	s_add_u32 s12, s12, 0xf0000
	s_addc_u32 s13, s13, 0
	global_load_dwordx4 v[72:75], v[20:21], off
	v_lshl_add_u64 v[22:23], v[8:9], 0, s[12:13]
	s_add_u32 s12, s12, 0xf0000
	s_addc_u32 s13, s13, 0
	global_load_dwordx4 v[76:79], v[22:23], off
	v_lshl_add_u64 v[20:21], v[8:9], 0, s[12:13]
	s_add_u32 s12, s12, 0xf0000
	s_addc_u32 s13, s13, 0
	global_load_dwordx4 v[80:83], v[20:21], off
	v_lshl_add_u64 v[22:23], v[8:9], 0, s[12:13]
	s_add_u32 s12, s12, 0xf0000
	s_addc_u32 s13, s13, 0
	global_load_dwordx4 v[84:87], v[22:23], off
	v_lshl_add_u64 v[20:21], v[8:9], 0, s[12:13]
	s_add_u32 s12, s12, 0xf0000
	s_addc_u32 s13, s13, 0
	global_load_dwordx4 v[88:91], v[20:21], off
	v_lshl_add_u64 v[22:23], v[8:9], 0, s[12:13]
	s_add_u32 s12, s12, 0xf0000
	s_addc_u32 s13, s13, 0
	global_load_dwordx4 v[92:95], v[22:23], off
	v_lshl_add_u64 v[20:21], v[8:9], 0, s[12:13]
	s_add_u32 s12, s12, 0xf0000
	s_addc_u32 s13, s13, 0
	global_load_dwordx4 v[96:99], v[20:21], off
	v_lshl_add_u64 v[22:23], v[8:9], 0, s[12:13]
	s_add_u32 s12, s12, 0xf0000
	s_addc_u32 s13, s13, 0
	global_load_dwordx4 v[100:103], v[22:23], off
	v_lshl_add_u64 v[20:21], v[8:9], 0, s[12:13]
	s_add_u32 s12, s12, 0xf0000
	s_addc_u32 s13, s13, 0
	global_load_dwordx4 v[104:107], v[20:21], off
	v_lshl_add_u64 v[22:23], v[8:9], 0, s[12:13]
	s_add_u32 s12, s12, 0xf0000
	s_addc_u32 s13, s13, 0
	global_load_dwordx4 v[108:111], v[22:23], off
	v_lshl_add_u64 v[20:21], v[8:9], 0, s[12:13]
	s_add_u32 s12, s12, 0xf0000
	s_addc_u32 s13, s13, 0
	global_load_dwordx4 v[112:115], v[20:21], off
	v_lshl_add_u64 v[22:23], v[8:9], 0, s[12:13]
	s_add_u32 s12, s12, 0xf0000
	s_addc_u32 s13, s13, 0
	global_load_dwordx4 v[116:119], v[22:23], off
	v_lshl_add_u64 v[20:21], v[8:9], 0, s[12:13]
	s_add_u32 s12, s12, 0xf0000
	s_addc_u32 s13, s13, 0
	global_load_dwordx4 v[120:123], v[20:21], off
	v_lshl_add_u64 v[22:23], v[8:9], 0, s[12:13]
	s_add_u32 s12, s12, 0xf0000
	s_addc_u32 s13, s13, 0
	global_load_dwordx4 v[124:127], v[22:23], off
	v_lshl_add_u64 v[20:21], v[8:9], 0, s[12:13]
	s_add_u32 s12, s12, 0xf0000
	s_addc_u32 s13, s13, 0
	global_load_dwordx4 v[128:131], v[20:21], off
	v_lshl_add_u64 v[22:23], v[8:9], 0, s[12:13]
	s_add_u32 s12, s12, 0xf0000
	s_addc_u32 s13, s13, 0
	global_load_dwordx4 v[132:135], v[22:23], off
	v_lshl_add_u64 v[20:21], v[8:9], 0, s[12:13]
	s_add_u32 s12, s12, 0xf0000
	s_addc_u32 s13, s13, 0
	global_load_dwordx4 v[136:139], v[20:21], off
	v_lshl_add_u64 v[22:23], v[8:9], 0, s[12:13]
	s_add_u32 s12, s12, 0xf0000
	s_addc_u32 s13, s13, 0
	global_load_dwordx4 v[140:143], v[22:23], off
	v_lshl_add_u64 v[20:21], v[8:9], 0, s[12:13]
	s_add_u32 s12, s12, 0xf0000
	s_addc_u32 s13, s13, 0
	global_load_dwordx4 v[144:147], v[20:21], off
	v_lshl_add_u64 v[22:23], v[8:9], 0, s[12:13]
	s_add_u32 s12, s12, 0xf0000
	s_addc_u32 s13, s13, 0
	global_load_dwordx4 v[148:151], v[22:23], off
	v_lshl_add_u64 v[20:21], v[8:9], 0, s[12:13]
	s_add_u32 s12, s12, 0xf0000
	s_addc_u32 s13, s13, 0
	global_load_dwordx4 v[152:155], v[20:21], off
	v_lshl_add_u64 v[22:23], v[8:9], 0, s[12:13]
	global_load_dwordx4 v[156:159], v[22:23], off
	s_waitcnt vmcnt(31)
	v_pk_add_f32 v[4:5], v[4:5], v[34:35]
	v_pk_add_f32 v[2:3], v[2:3], v[32:33]
	s_waitcnt vmcnt(30)
	v_pk_add_f32 v[4:5], v[4:5], v[38:39]
	v_pk_add_f32 v[2:3], v[2:3], v[36:37]
	s_waitcnt vmcnt(29)
	v_pk_add_f32 v[4:5], v[4:5], v[42:43]
	v_pk_add_f32 v[2:3], v[2:3], v[40:41]
	s_waitcnt vmcnt(28)
	v_pk_add_f32 v[4:5], v[4:5], v[46:47]
	v_pk_add_f32 v[2:3], v[2:3], v[44:45]
	s_waitcnt vmcnt(27)
	v_pk_add_f32 v[4:5], v[4:5], v[50:51]
	v_pk_add_f32 v[2:3], v[2:3], v[48:49]
	s_waitcnt vmcnt(26)
	v_pk_add_f32 v[4:5], v[4:5], v[54:55]
	v_pk_add_f32 v[2:3], v[2:3], v[52:53]
	s_waitcnt vmcnt(25)
	v_pk_add_f32 v[4:5], v[4:5], v[58:59]
	v_pk_add_f32 v[2:3], v[2:3], v[56:57]
	s_waitcnt vmcnt(24)
	v_pk_add_f32 v[4:5], v[4:5], v[62:63]
	v_pk_add_f32 v[2:3], v[2:3], v[60:61]
	s_waitcnt vmcnt(23)
	v_pk_add_f32 v[4:5], v[4:5], v[66:67]
	v_pk_add_f32 v[2:3], v[2:3], v[64:65]
	s_waitcnt vmcnt(22)
	v_pk_add_f32 v[4:5], v[4:5], v[70:71]
	v_pk_add_f32 v[2:3], v[2:3], v[68:69]
	s_waitcnt vmcnt(21)
	v_pk_add_f32 v[4:5], v[4:5], v[74:75]
	v_pk_add_f32 v[2:3], v[2:3], v[72:73]
	s_waitcnt vmcnt(20)
	v_pk_add_f32 v[4:5], v[4:5], v[78:79]
	v_pk_add_f32 v[2:3], v[2:3], v[76:77]
	s_waitcnt vmcnt(19)
	v_pk_add_f32 v[4:5], v[4:5], v[82:83]
	v_pk_add_f32 v[2:3], v[2:3], v[80:81]
	s_waitcnt vmcnt(18)
	v_pk_add_f32 v[4:5], v[4:5], v[86:87]
	v_pk_add_f32 v[2:3], v[2:3], v[84:85]
	s_waitcnt vmcnt(17)
	v_pk_add_f32 v[4:5], v[4:5], v[90:91]
	v_pk_add_f32 v[2:3], v[2:3], v[88:89]
	s_waitcnt vmcnt(16)
	v_pk_add_f32 v[4:5], v[4:5], v[94:95]
	v_pk_add_f32 v[2:3], v[2:3], v[92:93]
	s_waitcnt vmcnt(15)
	v_pk_add_f32 v[4:5], v[4:5], v[98:99]
	v_pk_add_f32 v[2:3], v[2:3], v[96:97]
	s_waitcnt vmcnt(14)
	v_pk_add_f32 v[4:5], v[4:5], v[102:103]
	v_pk_add_f32 v[2:3], v[2:3], v[100:101]
	s_waitcnt vmcnt(13)
	v_pk_add_f32 v[4:5], v[4:5], v[106:107]
	v_pk_add_f32 v[2:3], v[2:3], v[104:105]
	s_waitcnt vmcnt(12)
	v_pk_add_f32 v[4:5], v[4:5], v[110:111]
	v_pk_add_f32 v[2:3], v[2:3], v[108:109]
	s_waitcnt vmcnt(11)
	v_pk_add_f32 v[4:5], v[4:5], v[114:115]
	v_pk_add_f32 v[2:3], v[2:3], v[112:113]
	s_waitcnt vmcnt(10)
	v_pk_add_f32 v[4:5], v[4:5], v[118:119]
	v_pk_add_f32 v[2:3], v[2:3], v[116:117]
	s_waitcnt vmcnt(9)
	v_pk_add_f32 v[4:5], v[4:5], v[122:123]
	v_pk_add_f32 v[2:3], v[2:3], v[120:121]
	s_waitcnt vmcnt(8)
	v_pk_add_f32 v[4:5], v[4:5], v[126:127]
	v_pk_add_f32 v[2:3], v[2:3], v[124:125]
	s_waitcnt vmcnt(7)
	v_pk_add_f32 v[4:5], v[4:5], v[130:131]
	v_pk_add_f32 v[2:3], v[2:3], v[128:129]
	s_waitcnt vmcnt(6)
	v_pk_add_f32 v[4:5], v[4:5], v[134:135]
	v_pk_add_f32 v[2:3], v[2:3], v[132:133]
	s_waitcnt vmcnt(5)
	v_pk_add_f32 v[4:5], v[4:5], v[138:139]
	v_pk_add_f32 v[2:3], v[2:3], v[136:137]
	s_waitcnt vmcnt(4)
	v_pk_add_f32 v[4:5], v[4:5], v[142:143]
	v_pk_add_f32 v[2:3], v[2:3], v[140:141]
	s_waitcnt vmcnt(3)
	v_pk_add_f32 v[4:5], v[4:5], v[146:147]
	v_pk_add_f32 v[2:3], v[2:3], v[144:145]
	s_waitcnt vmcnt(2)
	v_pk_add_f32 v[4:5], v[4:5], v[150:151]
	v_pk_add_f32 v[2:3], v[2:3], v[148:149]
	s_waitcnt vmcnt(1)
	v_pk_add_f32 v[4:5], v[4:5], v[154:155]
	v_pk_add_f32 v[2:3], v[2:3], v[152:153]
	s_waitcnt vmcnt(0)
	v_pk_add_f32 v[4:5], v[4:5], v[158:159]
	v_pk_add_f32 v[2:3], v[2:3], v[156:157]
	v_mul_hi_i32_i24_e32 v9, 0xc000, v10
	v_mul_i32_i24_e32 v8, 0xc000, v10
	v_add_u32_e32 v1, s14, v1
	v_lshl_add_u64 v[8:9], s[8:9], 0, v[8:9]
	v_cmp_lt_i32_e32 vcc, s18, v1
	v_lshl_add_u64 v[6:7], v[6:7], 2, v[8:9]
	s_or_b64 s[10:11], vcc, s[10:11]
	global_store_dwordx4 v[6:7], v[2:5], off
	s_andn2_b64 exec, exec, s[10:11]
	s_cbranch_execnz .LBB0_837
